# speedup vs baseline: 1.0108x; 1.0108x over previous
; __device__ __forceinline__ int v_rd_base(int lane) { return ((lane & 3) << 3) | (((lane >> 2) & 3) << 6) | (((lane >> 4) & 1) << 5) | (((lane >> 5) & 1) << 8); }
; __device__ __forceinline__ const bf16* p32(const bf16* base, unsigned elem_off) { return (const bf16*)((const char*)base + (size_t)(elem_off * 2u)); }
; __device__ __forceinline__ float gate_of(const Params& p, const LaneId& L, int b) { return sigmoid_f(ldbf(p32(p.P, (unsigned)(L.tq * LDP + C_GT + L.h * 3 + b)))); }
; template <int MODE>
; __device__ __forceinline__ void nsa_single(const Params& p, const LaneId& L, int q0, int g, int ntiles, int first, char* smem, const bf16x8* qr, float gate, f32x16* o) {
;   const int NEG = -100000;
;   const unsigned char* ulist = (const unsigned char*)(smem + NSA_LIST);
;   const unsigned* mysel = (const unsigned*)(smem + NSA_SEL) + (L.wid * 8 + L.qi) * 8;
;   float* fac = (float*)(smem + NSA_FAC) + L.wid * 32;
;   char* pk = smem + NSA_IMP + L.wid * 8192;
;   const bf16* Kg; const bf16* Vg; const int ld = 128;
;   if (MODE == 1) { Kg = p.kvh + (long)(0 + g) * T * 128; Vg = p.kvh + (long)(4 + g) * T * 128; }
;   else { Kg = p.kvh + (long)(8 + g) * T * 128; Vg = p.kvh + (long)(12 + g) * T * 128; }
;   auto tile_row = [&](int i) -> int { const int ii = ntiles - 1 - i; if (MODE == 1) return __builtin_amdgcn_readfirstlane((int)ulist[ii]) * 64; return q0 - 512 + 64 * (first + ii); };
;   const int vb0 = (int)(uintptr_t)(smem + NSA_V0) + v_rd_base(L.lane);
;   float m = -1e30f, l = 0.f;
;   if (ntiles > 0) { const int row = tile_row(0); dma_k(Kg + (long)row * ld, ld, smem + NSA_K0, L.tid); dma_v(Vg + (long)row * ld, ld, smem + NSA_V0, L.tid); }
; __device__ void nsa_item(const Params& p, int qb, int g, char* smem) {
;     ...
;     const LaneId L = lane_id(q0, g);
;     park_o(o, smem + NSA_IMP + L.wid * 8192, L.lane);
; #pragma unroll
;     for (int d0 = 0; d0 < 4; ++d0) o[d0] = f32x16{};
;     { const unsigned qo = (unsigned)(L.tq * LDP + C_Q + L.h * 128 + L.hi * 8);
; #pragma unroll
;       for (int d0 = 0; d0 < 8; ++d0) qr[d0] = ld8(p32(p.P, qo + d0 * 16)); }
;     nsa_single<1>(p, L, q0, g, nsel, 0, smem, qr, gate_of(p, L, 1), o);
.LBB0_312:
	s_or_b64 exec, exec, s[8:9]
	v_add_u32_e32 v2, v73, v72
	v_add_u32_e32 v2, v2, v74
	v_add_u32_e32 v2, v2, v75
	v_add_u32_e32 v2, v2, v68
	v_mov_b32_e32 v145, v1
	v_add_u32_e32 v2, v2, v69
	s_waitcnt lgkmcnt(0)
	s_barrier
	v_cvt_pk_bf16_f32 v4, v4, v5
	v_ashrrev_i32_e32 v69, 6, v145
	v_and_b32_e32 v143, 63, v145
	v_lshl_add_u32 v141, v69, 13, v179
	v_lshlrev_b32_e32 v142, 3, v143
	v_cvt_pk_bf16_f32 v5, v6, v7
	v_or_b32_e32 v72, v141, v142
	v_cvt_pk_bf16_f32 v6, v8, v9
	v_cvt_pk_bf16_f32 v7, v10, v11
	ds_write2st64_b64 v72, v[4:5], v[6:7] offset1:1
	v_cvt_pk_bf16_f32 v4, v12, v13
	v_cvt_pk_bf16_f32 v5, v14, v15
	v_cvt_pk_bf16_f32 v6, v16, v17
	v_cvt_pk_bf16_f32 v7, v18, v19
	ds_write2st64_b64 v72, v[4:5], v[6:7] offset0:2 offset1:3
	v_cvt_pk_bf16_f32 v4, v52, v53
	v_cvt_pk_bf16_f32 v5, v54, v55
	v_cvt_pk_bf16_f32 v6, v56, v57
	v_cvt_pk_bf16_f32 v7, v58, v59
	s_addk_i32 s0, 0xff20
	ds_write2st64_b64 v72, v[4:5], v[6:7] offset0:4 offset1:5
	v_cvt_pk_bf16_f32 v4, v60, v61
	v_cvt_pk_bf16_f32 v5, v62, v63
	v_cvt_pk_bf16_f32 v6, v64, v65
	v_cvt_pk_bf16_f32 v7, v66, v67
	s_lshl_b32 s0, -1, s0
	ds_write2st64_b64 v72, v[4:5], v[6:7] offset0:6 offset1:7
	v_cvt_pk_bf16_f32 v4, v36, v37
	v_cvt_pk_bf16_f32 v5, v38, v39
	v_cvt_pk_bf16_f32 v6, v40, v41
	v_cvt_pk_bf16_f32 v7, v42, v43
	s_cmpk_gt_i32 s61, 0x383f
	ds_write2st64_b64 v72, v[4:5], v[6:7] offset0:8 offset1:9
	v_cvt_pk_bf16_f32 v4, v44, v45
	v_cvt_pk_bf16_f32 v5, v46, v47
	v_cvt_pk_bf16_f32 v6, v48, v49
	v_cvt_pk_bf16_f32 v7, v50, v51
	s_cselect_b32 s0, s0, -1
	ds_write2st64_b64 v72, v[4:5], v[6:7] offset0:10 offset1:11
	v_cvt_pk_bf16_f32 v4, v20, v21
	v_cvt_pk_bf16_f32 v5, v22, v23
	v_cvt_pk_bf16_f32 v6, v24, v25
	v_cvt_pk_bf16_f32 v7, v26, v27
	v_and_b32_e32 v68, s0, v71
	ds_write2st64_b64 v72, v[4:5], v[6:7] offset0:12 offset1:13
	v_cvt_pk_bf16_f32 v4, v28, v29
	v_cvt_pk_bf16_f32 v5, v30, v31
	v_cvt_pk_bf16_f32 v6, v32, v33
	v_cvt_pk_bf16_f32 v7, v34, v35
	v_bcnt_u32_b32 v68, v68, 0
	v_lshl_add_u32 v71, v69, 3, s5
	ds_write2st64_b64 v72, v[4:5], v[6:7] offset0:14 offset1:15
	v_bfe_u32 v6, v145, 2, 3
	v_add_u32_e32 v2, v2, v68
	v_or_b32_e32 v148, v71, v6
	v_add_u32_e32 v2, v2, v70
	v_bfe_u32 v68, v145, 5, 1
	v_and_or_b32 v70, v145, 3, s17
	v_mul_lo_u32 v7, v148, s33
	v_lshlrev_b32_e32 v5, 4, v68
	v_lshl_add_u32 v7, v70, 8, v7
	v_or_b32_e32 v7, v7, v5
	global_load_dwordx4 v[100:103], v7, s[46:47]
	global_load_dwordx4 v[104:107], v7, s[46:47] offset:32
	global_load_dwordx4 v[108:111], v7, s[46:47] offset:64
	global_load_dwordx4 v[112:115], v7, s[46:47] offset:96
	global_load_dwordx4 v[116:119], v7, s[46:47] offset:128
	global_load_dwordx4 v[120:123], v7, s[46:47] offset:160
	global_load_dwordx4 v[124:127], v7, s[46:47] offset:192
	global_load_dwordx4 v[128:131], v7, s[46:47] offset:224
	s_movk_i32 s25, 0x3100
	v_readfirstlane_b32 s0, v2
	v_mul_lo_u32 v2, v148, s25
	v_mad_u64_u32 v[8:9], s[2:3], v70, 3, v[2:3]
	v_lshl_add_u32 v2, v8, 1, v188
	global_load_ushort v144, v2, s[46:47]
	v_and_b32_e32 v4, 31, v145
	v_lshl_add_u32 v2, v69, 7, v189
	s_cmp_lt_i32 s0, 1
	v_cmp_gt_u32_e64 s[8:9], 32, v143
	v_lshl_add_u32 v147, v4, 2, v2
	v_lshl_add_u32 v146, v68, 4, v2
	s_cbranch_scc1 .LBB0_336
	s_lshl_b64 s[2:3], s[96:97], 22
	s_add_u32 s1, s34, s2
	s_addc_u32 s24, s35, s3
	s_sub_i32 s18, 7, s16
	s_lshl_b64 s[2:3], s[18:19], 22
	s_add_u32 s18, s34, s2
	s_addc_u32 s25, s35, s3
	s_add_i32 s2, s0, 0x20c1f
	v_mov_b32_e32 v2, s2
	ds_read_u8 v2, v2
	v_lshrrev_b32_e32 v8, 5, v145
	v_and_b32_e32 v7, 15, v145
	v_and_b32_e32 v9, 8, v8
	v_readfirstlane_b32 s12, v145
	s_waitcnt lgkmcnt(0)
	v_readfirstlane_b32 s2, v2
	v_ashrrev_i32_e32 v2, 4, v145
	v_and_b32_e32 v10, 7, v2
	v_bitop3_b32 v10, v10, v7, v9 bitop3:0x36
	v_lshlrev_b32_e32 v2, 8, v2
	v_lshl_or_b32 v2, v10, 4, v2
	v_add_u32_e32 v10, 0x200, v145
	s_lshl_b32 s2, s2, 6
	v_ashrrev_i32_e32 v10, 4, v10
	s_ashr_i32 s3, s2, 31
	v_and_b32_e32 v11, 7, v10
	s_lshl_b64 s[2:3], s[2:3], 8
	v_bitop3_b32 v7, v11, v7, v9 bitop3:0x36
	v_lshlrev_b32_e32 v9, 8, v10
	s_add_u32 s10, s1, s2
	v_lshl_or_b32 v132, v7, 4, v9
	v_and_b32_e32 v7, 0x60, v145
	v_lshlrev_b32_e32 v9, 3, v145
	s_addc_u32 s11, s24, s3
	s_lshl_b32 s12, s12, 4
	v_and_or_b32 v7, v9, 24, v7
	v_bfe_u32 v9, v145, 2, 2
	s_and_b32 s12, s12, 0xfffffc00
	v_and_or_b32 v8, v8, 4, v9
	v_lshrrev_b32_e32 v9, 4, v145
	v_lshrrev_b32_e32 v10, 1, v145
	s_mov_b32 m0, s12
	v_and_b32_e32 v9, 48, v9
	v_and_b32_e32 v10, 8, v10
	global_load_lds_dwordx4 v2, s[10:11]
	s_add_i32 m0, s12, 0x2000
	v_or3_b32 v8, v8, v9, v10
	s_add_u32 s2, s18, s2
	v_lshlrev_b32_e32 v8, 8, v8
	v_lshlrev_b32_e32 v7, 1, v7
	global_load_lds_dwordx4 v132, s[10:11]
	s_addc_u32 s3, s25, s3
	v_or_b32_e32 v134, v8, v7
	s_add_i32 m0, s12, 0x8000
	s_movk_i32 s10, 0x2000
	global_load_lds_dwordx4 v134, s[2:3]
	v_bitop3_b32 v136, v8, s10, v7 bitop3:0x36
	s_add_i32 m0, s12, 0xa000
	v_add_u32_e32 v7, 1, v70
	global_load_lds_dwordx4 v136, s[2:3]
	v_cvt_f32_u32_e32 v7, v7
	s_mov_b32 s2, 0xc2fc0000
	v_lshlrev_b32_e32 v152, 8, v4
	v_and_or_b32 v4, v145, 7, v10
	v_mul_f32_e32 v8, -0.5, v7
	v_cmp_gt_f32_e32 vcc, s2, v8
	v_lshlrev_b32_e32 v4, 4, v4
	s_movk_i32 s2, 0x60
	v_cndmask_b32_e32 v8, 0, v180, vcc
	v_fmac_f32_e32 v8, -0.5, v7
	v_exp_f32_e32 v7, v8
	v_bitop3_b32 v156, v4, v5, s2 bitop3:0x1e
	s_movk_i32 s2, 0x80
	v_cndmask_b32_e32 v8, 0, v181, vcc
	v_lshlrev_b32_e32 v6, 5, v6
	v_bitop3_b32 v157, v4, v5, s2 bitop3:0x1e
	s_movk_i32 s2, 0xa0
	v_ldexp_f32 v7, v7, v8
	v_lshl_or_b32 v6, v69, 8, v6
	v_bitop3_b32 v158, v4, v5, s2 bitop3:0x1e
	s_movk_i32 s2, 0xc0
	v_mul_f32_e32 v138, 0x3fb8aa3b, v7
	v_add_u32_e32 v149, 0x20400, v6
	v_lshlrev_b32_e32 v6, 1, v143
; __device__ __forceinline__ int v_rd_base(int lane) { return ((lane & 3) << 3) | (((lane >> 2) & 3) << 6) | (((lane >> 4) & 1) << 5) | (((lane >> 5) & 1) << 8); }
; template <int MODE>
; __device__ __forceinline__ void nsa_single(const Params& p, const LaneId& L, int q0, int g, int ntiles, int first, char* smem, const bf16x8* qr, float gate, f32x16* o) {
;     ...
;   const int vb0 = (int)(uintptr_t)(smem + NSA_V0) + v_rd_base(L.lane);
;   float m = -1e30f, l = 0.f;
;   if (ntiles > 0) { const int row = tile_row(0); dma_k(Kg + (long)row * ld, ld, smem + NSA_K0, L.tid); dma_v(Vg + (long)row * ld, ld, smem + NSA_V0, L.tid); }
; #pragma unroll 1
;   for (int i = 0; i < ntiles; ++i) {
;     const int row = tile_row(i), buf = i & 1;
;     char* Kl = smem + NSA_K0 + buf * 16384;
;     asm volatile("s_waitcnt vmcnt(0)" ::: "memory");
;     __syncthreads();
;     if (i + 1 < ntiles) { const int rn = tile_row(i + 1); dma_k(Kg + (long)rn * ld, ld, smem + NSA_K0 + (buf ^ 1) * 16384, L.tid); dma_v(Vg + (long)rn * ld, ld, smem + NSA_V0 + (buf ^ 1) * 16384, L.tid); }
;     int pb = row, lo, hl; float badd = 0.f;
;     if (MODE == 1) { const int j = row >> 6; lo = NEG; const bool fl = ((mysel[j >> 5] >> (j & 31)) & 1u) != 0u;
;       if (row == q0) hl = fl ? (L.tq - pb) : NEG; else { hl = 1000; badd = fl ? 0.f : -INFINITY; } }
;     else { lo = L.tq - 512 - pb; hl = L.tq - pb; }
;     constexpr float C = 0.08838834764831845f * LOG2E;
;     const float A1 = L.sl2; const float B1 = L.sl2 * (float)(pb - L.tq) + A1 * (float)(4 * L.hi) + badd;
;     const int lo2 = lo - 4 * L.hi, hl2 = hl - 4 * L.hi;
;     const bool nomask = __all(lo2 < 0 && hl2 >= 63);
	v_lshlrev_b32_e32 v7, 4, v143
	v_and_b32_e32 v8, 0x118, v142
	v_lshlrev_b32_e32 v150, 2, v68
	v_bitop3_b32 v159, v4, v5, s2 bitop3:0x1e
	s_movk_i32 s2, 0xe0
	v_and_b32_e32 v7, 0xc0, v7
	v_cvt_f32_ubyte0_e32 v9, v150
	v_xor_b32_e32 v153, v4, v5
	v_bitop3_b32 v154, v4, v5, 32 bitop3:0x1e
	v_bitop3_b32 v155, v4, v5, 64 bitop3:0x1e
	v_bitop3_b32 v160, v4, v5, s2 bitop3:0x1e
	v_and_or_b32 v4, v6, 32, v8
	v_mov_b32_e32 v52, v3
	v_mov_b32_e32 v53, v3
	v_mul_f32_e32 v151, v138, v9
	v_or3_b32 v161, v7, v4, s23
	v_mov_b32_e32 v54, v3
	v_mov_b32_e32 v55, v3
	v_mov_b32_e32 v56, v3
	v_mov_b32_e32 v57, v3
	v_mov_b32_e32 v58, v3
	v_mov_b32_e32 v59, v3
	v_mov_b32_e32 v60, v3
	v_mov_b32_e32 v61, v3
	v_mov_b32_e32 v62, v3
	v_mov_b32_e32 v63, v3
	v_mov_b32_e32 v64, v3
	v_mov_b32_e32 v65, v3
	v_mov_b32_e32 v66, v3
	v_mov_b32_e32 v67, v3
	v_mov_b64_e32 v[36:37], v[52:53]
	v_mov_b64_e32 v[20:21], v[52:53]
	v_mov_b64_e32 v[4:5], v[52:53]
	s_mov_b32 s61, 1
	s_mov_b32 s97, 0
	v_mov_b32_e32 v133, v3
	v_mov_b32_e32 v135, v3
	v_mov_b32_e32 v137, v3
	v_mov_b32_e32 v139, v138
	v_mov_b32_e32 v162, 0
	v_mov_b32_e32 v165, 0xf149f2ca
	s_mov_b32 s26, s0
	v_mov_b64_e32 v[38:39], v[54:55]
	v_mov_b64_e32 v[40:41], v[56:57]
	v_mov_b64_e32 v[42:43], v[58:59]
	v_mov_b64_e32 v[44:45], v[60:61]
	v_mov_b64_e32 v[46:47], v[62:63]
	v_mov_b64_e32 v[48:49], v[64:65]
	v_mov_b64_e32 v[50:51], v[66:67]
	v_mov_b64_e32 v[22:23], v[54:55]
	v_mov_b64_e32 v[24:25], v[56:57]
	v_mov_b64_e32 v[26:27], v[58:59]
	v_mov_b64_e32 v[28:29], v[60:61]
	v_mov_b64_e32 v[30:31], v[62:63]
	v_mov_b64_e32 v[32:33], v[64:65]
	v_mov_b64_e32 v[34:35], v[66:67]
	v_mov_b64_e32 v[6:7], v[54:55]
	v_mov_b64_e32 v[8:9], v[56:57]
	v_mov_b64_e32 v[10:11], v[58:59]
	v_mov_b64_e32 v[12:13], v[60:61]
	v_mov_b64_e32 v[14:15], v[62:63]
	v_mov_b64_e32 v[16:17], v[64:65]
	v_mov_b64_e32 v[18:19], v[66:67]
	s_waitcnt vmcnt(0)
	v_mov_b32_e32 v226, 0
	v_mul_f32_e32 v227, 0x40faf232, v138
	v_mul_f32_e32 v228, 0x417af232, v138
	v_mul_f32_e32 v229, 0x41bc35a6, v138
	v_mul_f32_e32 v230, 0x427af232, v138
	v_mul_f32_e32 v231, 0x428d283c, v138
	v_mul_f32_e32 v232, 0x429cd760, v138
	v_mul_f32_e32 v233, 0x42ac8683, v138
	v_mul_f32_e32 v234, 0x42faf232, v138
	v_mul_f32_e32 v235, 0x430550ab, v138
	v_mul_f32_e32 v236, 0x430d283c, v138
	v_mul_f32_e32 v237, 0x4314ffce, v138
	v_mul_f32_e32 v238, 0x433c35a6, v138
	v_mul_f32_e32 v239, 0x43440d37, v138
	v_mul_f32_e32 v240, 0x434be4c9, v138
	v_mul_f32_e32 v241, 0x4353bc5b, v138
	s_add_i32 s2, s26, 0x20c1f
	v_mov_b32_e32 v68, s2
	ds_read_u8 v68, v68
	s_waitcnt lgkmcnt(0)
	v_readfirstlane_b32 s100, v68
	s_branch .LBB0_316
.LBB0_316:
	s_add_i32 s3, s26, 0x20c1e
	v_mov_b32_e32 v68, s3
	ds_read_u8 v68, v68
	s_ashr_i32 s2, s100, 5
	v_lshl_add_u32 v73, s2, 2, v149
	ds_read_b32 v72, v73
	s_waitcnt vmcnt(0)
	s_and_b32 s22, s97, 0x4000
	s_cmp_ge_i32 s61, s0
	s_mov_b32 s2, s100
	s_barrier
	v_add_u32_e32 v242, s22, v152
	v_add_u32_e32 v248, s22, v161
	v_add_u32_e32 v249, v242, v153
	ds_read_b128 v[84:87], v249
	v_add_u32_e32 v251, v242, v154
	ds_read_b128 v[88:91], v251
	v_add_u32_e32 v249, v242, v155
	ds_read_b128 v[92:95], v249
	v_add_u32_e32 v251, v242, v156
	ds_read_b128 v[96:99], v251
	v_add_u32_e32 v249, v242, v157
	ds_read_b128 v[194:197], v249
	v_add_u32_e32 v251, v242, v158
	ds_read_b128 v[198:201], v251
	v_add_u32_e32 v249, v242, v159
	ds_read_b128 v[202:205], v249
	v_add_u32_e32 v251, v242, v160
	ds_read_b128 v[206:209], v251
	s_cbranch_scc1 .LBB0_318
	v_readfirstlane_b32 s3, v145
	s_waitcnt lgkmcnt(8)
	v_readfirstlane_b32 s10, v68
	s_mov_b32 s100, s10
	s_lshl_b32 s10, s10, 6
	s_ashr_i32 s11, s10, 31
	s_lshl_b64 s[10:11], s[10:11], 8
	s_add_u32 s12, s1, s10
	s_addc_u32 s13, s24, s11
	s_lshl_b32 s3, s3, 4
	s_xor_b32 s27, s22, 0x4000
	s_and_b32 s3, s3, 0xfffffc00
	s_add_i32 s3, s27, s3
	v_lshl_add_u64 v[68:69], s[12:13], 0, v[2:3]
	s_mov_b32 m0, s3
	s_nop 0
	global_load_lds_dwordx4 v[68:69], off
	s_add_i32 m0, s3, 0x2000
	s_add_u32 s10, s18, s10
	v_lshl_add_u64 v[68:69], s[12:13], 0, v[132:133]
	s_addc_u32 s11, s25, s11
	global_load_lds_dwordx4 v[68:69], off
	v_lshl_add_u64 v[68:69], s[10:11], 0, v[134:135]
	s_add_i32 m0, s3, 0x8000
	s_nop 0
	global_load_lds_dwordx4 v[68:69], off
	v_lshl_add_u64 v[68:69], s[10:11], 0, v[136:137]
	s_add_i32 m0, s3, 0xa000
	s_nop 0
	global_load_lds_dwordx4 v[68:69], off
; #define KSWZ(row, colB) ((row) * 256 + ((colB) ^ (KSWZF(row) << 4)))
; #define SBAR() __builtin_amdgcn_sched_barrier(0)
; template <int H> __device__ __forceinline__ void qkt_half(f32x16& pz, const char* Ks, const bf16x8* qr, int r32, int hi) {
;   bf16x8 kf[8];
; #pragma unroll
;   for (int d0 = 0; d0 < 8; ++d0) { const int cb = (d0 * 16 + hi * 8) * 2; kf[d0] = *reinterpret_cast<const bf16x8*>(Ks + KSWZ(32 * H + r32, cb)); }
;   asm volatile("s_waitcnt lgkmcnt(0)" ::: "memory"); SBAR();
;   f32x16 pb = {};
; #pragma unroll
;   for (int d0 = 0; d0 < 8; d0 += 2) {
;     pz = __builtin_amdgcn_mfma_f32_32x32x16_bf16(kf[d0], qr[d0], pz, 0, 0, 0);
;     pb = __builtin_amdgcn_mfma_f32_32x32x16_bf16(kf[d0 + 1], qr[d0 + 1], pb, 0, 0, 0); }
; #pragma unroll
;   for (int r = 0; r < 16; ++r) pz[r] += pb[r];
; template <int MODE>
; __device__ __forceinline__ void nsa_single(const Params& p, const LaneId& L, int q0, int g, int ntiles, int first, char* smem, const bf16x8* qr, float gate, f32x16* o) {
;     ...
;     if (MODE == 1) { const int j = row >> 6; lo = NEG; const bool fl = ((mysel[j >> 5] >> (j & 31)) & 1u) != 0u;
;       if (row == q0) hl = fl ? (L.tq - pb) : NEG; else { hl = 1000; badd = fl ? 0.f : -INFINITY; } }
;     else { lo = L.tq - 512 - pb; hl = L.tq - pb; }
;     constexpr float C = 0.08838834764831845f * LOG2E;
;     const float A1 = L.sl2; const float B1 = L.sl2 * (float)(pb - L.tq) + A1 * (float)(4 * L.hi) + badd;
;     const int lo2 = lo - 4 * L.hi, hl2 = hl - 4 * L.hi;
;     const bool nomask = __all(lo2 < 0 && hl2 >= 63);
.LBB0_318:
	s_lshl_b32 s3, s2, 6
	s_and_b32 s2, s2, 31
	v_sub_u32_e32 v74, s3, v148
	v_cvt_f32_i32_e32 v74, v74
	s_waitcnt lgkmcnt(8)
	v_bfe_u32 v72, v72, s2, 1
	s_cmp_eq_u32 s3, s5
	v_subrev_u32_e32 v73, s3, v148
	v_cmp_eq_u32_e32 vcc, 0, v72
	v_fma_f32 v74, v138, v74, v151
	s_nop 1
	v_cndmask_b32_e32 v72, v73, v190, vcc
	v_cndmask_b32_e32 v73, 0, v183, vcc
	s_cselect_b64 vcc, -1, 0
	v_cndmask_b32_e32 v72, v191, v72, vcc
	v_cndmask_b32_e64 v73, v73, 0, vcc
	v_sub_u32_e32 v163, v72, v150
	v_add_f32_e32 v140, v74, v73
	v_cmp_lt_i32_e32 vcc, 62, v163
	s_nop 3
	s_cmp_lg_u64 vcc, exec
	s_cselect_b64 s[98:99], -1, 0
	v_add_f32_e32 v243, 0x41000000, v165
	v_mov_b32_e32 v250, v140
	s_waitcnt lgkmcnt(7)
	v_mfma_f32_32x32x16_bf16 v[68:83], v[84:87], v[100:103], v[226:241]
	v_add_u32_e32 v249, v242, v153
	ds_read_b128 v[84:87], v249 offset:8192
	s_waitcnt lgkmcnt(7)
	v_mfma_f32_32x32x16_bf16 v[68:83], v[88:91], v[104:107], v[68:83]
	v_add_u32_e32 v251, v242, v154
	ds_read_b128 v[88:91], v251 offset:8192
	s_waitcnt lgkmcnt(7)
	v_mfma_f32_32x32x16_bf16 v[68:83], v[92:95], v[108:111], v[68:83]
	v_add_u32_e32 v249, v242, v155
	ds_read_b128 v[92:95], v249 offset:8192
	s_waitcnt lgkmcnt(7)
	v_mfma_f32_32x32x16_bf16 v[68:83], v[96:99], v[112:115], v[68:83]
	v_add_u32_e32 v251, v242, v156
	ds_read_b128 v[96:99], v251 offset:8192
	s_waitcnt lgkmcnt(7)
	v_mfma_f32_32x32x16_bf16 v[68:83], v[194:197], v[116:119], v[68:83]
	v_add_u32_e32 v249, v242, v157
	ds_read_b128 v[194:197], v249 offset:8192
	s_waitcnt lgkmcnt(7)
	v_mfma_f32_32x32x16_bf16 v[68:83], v[198:201], v[120:123], v[68:83]
	v_add_u32_e32 v251, v242, v158
	ds_read_b128 v[198:201], v251 offset:8192
	s_waitcnt lgkmcnt(7)
	v_mfma_f32_32x32x16_bf16 v[68:83], v[202:205], v[124:127], v[68:83]
	v_add_u32_e32 v249, v242, v159
	ds_read_b128 v[202:205], v249 offset:8192
	s_waitcnt lgkmcnt(7)
	v_mfma_f32_32x32x16_bf16 v[68:83], v[206:209], v[128:131], v[68:83]
	v_add_u32_e32 v251, v242, v160
	ds_read_b128 v[206:209], v251 offset:8192
	s_waitcnt lgkmcnt(7)
	v_mfma_f32_32x32x16_bf16 v[210:225], v[84:87], v[100:103], v[226:241]
	ds_read_b64_tr_b16 v[84:85], v248 offset:0
	ds_read_b64_tr_b16 v[86:87], v248 offset:2048
	s_waitcnt lgkmcnt(8)
	v_mfma_f32_32x32x16_bf16 v[210:225], v[88:91], v[104:107], v[210:225]
	ds_read_b64_tr_b16 v[88:89], v248 offset:4096
	ds_read_b64_tr_b16 v[90:91], v248 offset:6144
	s_waitcnt lgkmcnt(9)
	v_mfma_f32_32x32x16_bf16 v[210:225], v[92:95], v[108:111], v[210:225]
	ds_read_b64_tr_b16 v[92:93], v248 offset:512
	ds_read_b64_tr_b16 v[94:95], v248 offset:2560
	s_waitcnt lgkmcnt(10)
	v_mfma_f32_32x32x16_bf16 v[210:225], v[96:99], v[112:115], v[210:225]
	ds_read_b64_tr_b16 v[96:97], v248 offset:4608
	ds_read_b64_tr_b16 v[98:99], v248 offset:6656
	s_waitcnt lgkmcnt(11)
	v_mfma_f32_32x32x16_bf16 v[210:225], v[194:197], v[116:119], v[210:225]
	ds_read_b64_tr_b16 v[194:195], v248 offset:1024
	ds_read_b64_tr_b16 v[196:197], v248 offset:3072
	s_waitcnt lgkmcnt(12)
	v_mfma_f32_32x32x16_bf16 v[210:225], v[198:201], v[120:123], v[210:225]
	ds_read_b64_tr_b16 v[198:199], v248 offset:5120
	ds_read_b64_tr_b16 v[200:201], v248 offset:7168
	s_waitcnt lgkmcnt(13)
	v_mfma_f32_32x32x16_bf16 v[210:225], v[202:205], v[124:127], v[210:225]
	ds_read_b64_tr_b16 v[202:203], v248 offset:1536
	ds_read_b64_tr_b16 v[204:205], v248 offset:3584
	s_waitcnt lgkmcnt(14)
	v_mfma_f32_32x32x16_bf16 v[210:225], v[206:209], v[128:131], v[210:225]
	ds_read_b64_tr_b16 v[206:207], v248 offset:5632
	ds_read_b64_tr_b16 v[208:209], v248 offset:7680
	v_fmamk_f32 v251, v138, 0x42000000, v140
	s_and_b64 vcc, exec, s[98:99]
	s_cbranch_vccz .Lsel_nm
	v_cmp_lt_i32_e32 vcc, -1, v163
	v_cmp_lt_i32_e64 s[10:11], 0, v163
	v_cmp_lt_i32_e64 s[12:13], 1, v163
	v_cmp_lt_i32_e64 s[2:3], 2, v163
	s_nop 0
	v_cndmask_b32_e32 v68, v183, v68, vcc
	v_cndmask_b32_e64 v69, v183, v69, s[10:11]
	v_cndmask_b32_e64 v70, v183, v70, s[12:13]
	v_cndmask_b32_e64 v71, v183, v71, s[2:3]
	v_cmp_lt_i32_e32 vcc, 7, v163
	v_cmp_lt_i32_e64 s[10:11], 8, v163
	v_cmp_lt_i32_e64 s[12:13], 9, v163
	v_cmp_lt_i32_e64 s[2:3], 10, v163
	s_nop 0
	v_cndmask_b32_e32 v72, v183, v72, vcc
	v_cndmask_b32_e64 v73, v183, v73, s[10:11]
	v_cndmask_b32_e64 v74, v183, v74, s[12:13]
	v_cndmask_b32_e64 v75, v183, v75, s[2:3]
	v_cmp_lt_i32_e32 vcc, 15, v163
	v_cmp_lt_i32_e64 s[10:11], 16, v163
	v_cmp_lt_i32_e64 s[12:13], 17, v163
	v_cmp_lt_i32_e64 s[2:3], 18, v163
	s_nop 0
	v_cndmask_b32_e32 v76, v183, v76, vcc
	v_cndmask_b32_e64 v77, v183, v77, s[10:11]
	v_cndmask_b32_e64 v78, v183, v78, s[12:13]
	v_cndmask_b32_e64 v79, v183, v79, s[2:3]
	v_cmp_lt_i32_e32 vcc, 23, v163
	v_cmp_lt_i32_e64 s[10:11], 24, v163
	v_cmp_lt_i32_e64 s[12:13], 25, v163
	v_cmp_lt_i32_e64 s[2:3], 26, v163
	s_nop 0
	v_cndmask_b32_e32 v80, v183, v80, vcc
	v_cndmask_b32_e64 v81, v183, v81, s[10:11]
	v_cndmask_b32_e64 v82, v183, v82, s[12:13]
	v_cndmask_b32_e64 v83, v183, v83, s[2:3]
	v_cmp_lt_i32_e32 vcc, 31, v163
	v_cmp_lt_i32_e64 s[10:11], 32, v163
	v_cmp_lt_i32_e64 s[12:13], 33, v163
	v_cmp_lt_i32_e64 s[2:3], 34, v163
	s_nop 0
	v_cndmask_b32_e32 v210, v183, v210, vcc
	v_cndmask_b32_e64 v211, v183, v211, s[10:11]
	v_cndmask_b32_e64 v212, v183, v212, s[12:13]
	v_cndmask_b32_e64 v213, v183, v213, s[2:3]
	v_cmp_lt_i32_e32 vcc, 39, v163
	v_cmp_lt_i32_e64 s[10:11], 40, v163
	v_cmp_lt_i32_e64 s[12:13], 41, v163
	v_cmp_lt_i32_e64 s[2:3], 42, v163
	s_nop 0
	v_cndmask_b32_e32 v214, v183, v214, vcc
	v_cndmask_b32_e64 v215, v183, v215, s[10:11]
	v_cndmask_b32_e64 v216, v183, v216, s[12:13]
	v_cndmask_b32_e64 v217, v183, v217, s[2:3]
	v_cmp_lt_i32_e32 vcc, 47, v163
	v_cmp_lt_i32_e64 s[10:11], 48, v163
	v_cmp_lt_i32_e64 s[12:13], 49, v163
	v_cmp_lt_i32_e64 s[2:3], 50, v163
	s_nop 0
	v_cndmask_b32_e32 v218, v183, v218, vcc
	v_cndmask_b32_e64 v219, v183, v219, s[10:11]
	v_cndmask_b32_e64 v220, v183, v220, s[12:13]
	v_cndmask_b32_e64 v221, v183, v221, s[2:3]
	v_cmp_lt_i32_e32 vcc, 55, v163
	v_cmp_lt_i32_e64 s[10:11], 56, v163
	v_cmp_lt_i32_e64 s[12:13], 57, v163
	v_cmp_lt_i32_e64 s[2:3], 58, v163
	s_nop 0
	v_cndmask_b32_e32 v222, v183, v222, vcc
	v_cndmask_b32_e64 v223, v183, v223, s[10:11]
	v_cndmask_b32_e64 v224, v183, v224, s[12:13]
	v_cndmask_b32_e64 v225, v183, v225, s[2:3]
